# v_c4 + odd-layer in/out projection weight conversions (cd_in, cd_out: 8192 items) moved out of P0 into the idle halves of the even layers' scan and gate phases (re-entering P0's generic conversion loo
# speedup vs baseline: 1.0027x; 1.0027x over previous
; #define LAS __attribute__((address_space(3)))
; __global__ void __launch_bounds__(512, 2) fwd(Args args) {
;     extern __shared__ __attribute__((aligned(16))) unsigned char lds_raw[];
;     LAS unsigned char* lds = (LAS unsigned char*)lds_raw;
;     const int lo = args.ph_lo, hi = args.ph_hi;
;     const int wave_s = __builtin_amdgcn_readfirstlane((int)threadIdx.x >> 6);
;     ...
;     constexpr bool fusedln = false;
;     ...
;     constexpr bool fusedln = true;
;     ...
;     const unsigned rep_mask = args.rep;
;     ...
;     volatile LAS unsigned* MISC = (volatile LAS unsigned*)(lds + LDS_MISC);
;     if (threadIdx.x < 8) MISC[threadIdx.x] = 0u;
;     __syncthreads();
;     XcdBarrier bar; bar.bar = (unsigned*)(args.ws + WS_CTL) + CW_BAR; bar.x = 0; bar.st = nullptr; bar.wave = wave_s;
;     if (hi - lo > 1) { bar = xcd_barrier_post((unsigned*)(args.ws + WS_CTL) + CW_BAR, MISC); bar.wave = wave_s; }
_Z3fwd4Args:
	s_mov_b32 s101, 0
	s_load_dwordx4 s[92:95], s[0:1], 0x118
	s_mov_b64 s[90:91], s[0:1]
	v_writelane_b32 v253, s2, 0
	v_readfirstlane_b32 s38, v0
	v_cmp_gt_u32_e32 vcc, 8, v0
	v_writelane_b32 v253, s3, 1
	s_and_saveexec_b64 s[0:1], vcc
	v_lshl_add_u32 v1, v0, 2, 0
	v_add_u32_e32 v1, 0x23000, v1
	v_mov_b32_e32 v2, 0
	ds_write_b32 v1, v2
	s_or_b64 exec, exec, s[0:1]
	s_waitcnt lgkmcnt(0)
	s_add_u32 s96, s92, 0x4000
	s_addc_u32 s97, s93, 0
	s_sub_i32 s0, s95, s94
	s_cmp_lt_i32 s0, 2
	s_mov_b32 s0, 0
	s_mov_b32 s33, 0
	v_writelane_b32 v253, s0, 2
	s_barrier
	s_cbranch_scc1 .LBB0_7
	s_getreg_b32 s0, hwreg(HW_REG_XCC_ID, 0, 4)
	s_and_b32 s33, s0, 15
	v_cmp_eq_u32_e32 vcc, 0, v0
	s_and_saveexec_b64 s[0:1], vcc
	s_cbranch_execz .LBB0_6
	s_mov_b64 s[4:5], exec
	v_mbcnt_lo_u32_b32 v0, s4, 0
	v_mbcnt_hi_u32_b32 v0, s5, v0
	v_cmp_eq_u32_e32 vcc, 0, v0
	s_and_b64 s[6:7], exec, vcc
	s_mov_b64 exec, s[6:7]
	s_cbranch_execz .LBB0_6
	s_lshl_b32 s3, s33, 8
	s_bcnt1_i32_b64 s4, s[4:5]
	v_mov_b32_e32 v0, s3
	v_mov_b32_e32 v1, s4
	global_atomic_add v0, v1, s[96:97] offset:1024

.LBB0_30:
	v_readlane_b32 s0, v253, 0
	s_lshl_b32 s0, s0, 3
	s_add_i32 s3, s20, s0
	s_movk_i32 s100, 0x6a80
	s_cmp_lt_i32 s3, s100
	v_lshrrev_b32_e32 v133, 4, v64
	v_lshlrev_b32_e32 v0, 2, v64
	v_readlane_b32 s1, v253, 1
	s_cbranch_scc1 .LBB0_33
.Lp0_bb31:
	v_lshrrev_b32_e32 v1, 4, v64
	v_and_b32_e32 v144, 60, v0
	s_cbranch_execz .LBB0_34
	v_mov_b32_e32 v133, v1
	s_branch .LBB0_90

.LBB0_51:
	s_andn2_b64 vcc, exec, s[6:7]
	s_cbranch_vccnz .LBB0_53
	s_load_dwordx2 s[0:1], s[10:11], 0xd8
	s_add_i32 s8, s3, 0xffff9f80
	s_lshr_b32 s6, s8, 10
	s_mov_b32 s7, 0
	s_and_b32 s24, s8, 0x3ff
	s_lshl_b64 s[4:5], s[6:7], 24
	s_waitcnt lgkmcnt(0)
	s_add_u32 s4, s0, s4
	s_addc_u32 s5, s1, s5
	s_lshr_b32 s0, s8, 9
	s_or_b32 s6, s0, 1
	s_lshl_b64 s[0:1], s[6:7], 23
	s_add_u32 s0, s16, s0
	s_addc_u32 s1, s17, s1
	s_add_u32 s0, s0, 0x6200000
	s_addc_u32 s1, s1, 0
	s_cmp_eq_u32 s101, 0
	s_cselect_b32 s25, 0, 0x800
	s_mov_b32 s26, 32
	s_branch .LBB0_54

.LBB0_58:
	s_andn2_b64 vcc, exec, s[6:7]
	s_mov_b32 s27, s25
	s_cbranch_vccnz .LBB0_60
	s_add_i32 s6, s3, 0xffffbf80
	s_cmpk_gt_u32 s6, 0xbff
	s_cselect_b64 s[0:1], -1, 0
	s_and_b64 s[4:5], s[0:1], exec
	s_load_dwordx2 s[4:5], s[10:11], 0xd0
	s_cselect_b32 s7, 0xfffff400, 0
	s_add_i32 s24, s7, s6
	s_and_b64 s[6:7], s[0:1], exec
	s_cselect_b32 s6, 0x3000000, 0
	s_waitcnt lgkmcnt(0)
	s_add_u32 s4, s4, s6
	s_addc_u32 s5, s5, 0
	s_mov_b32 s6, 0x4800000
	s_and_b64 s[0:1], s[0:1], exec
	s_cselect_b32 s0, s6, 0x1800000
	s_add_u32 s0, s16, s0
	s_addc_u32 s1, s17, 0
	s_add_u32 s0, s0, 0x200000
	s_addc_u32 s1, s1, 0
	s_movk_i32 s27, 0x800
	s_cmp_eq_u32 s101, 0
	s_cselect_b32 s25, 0, 0x1800
	s_movk_i32 s26, 0x60

.LBB0_95:
	s_cmp_ge_i32 s3, s100
	s_mov_b64 s[16:17], -1
	s_cbranch_scc1 .LBB0_94
	s_add_i32 s3, s3, s29
	s_cmp_lt_i32 s3, s100
	s_cselect_b64 s[18:19], -1, 0
	s_cmp_ge_i32 s3, s100
	s_cselect_b64 s[16:17], -1, 0
	s_and_b64 vcc, exec, s[16:17]
	s_cbranch_vccnz .LBB0_147
	s_cmpk_gt_i32 s3, 0xaff
	s_mov_b64 s[22:23], -1
	s_cbranch_scc0 .LBB0_128
	s_cmpk_gt_u32 s3, 0x15ff
	s_cbranch_scc0 .LBB0_125
	s_cmpk_gt_u32 s3, 0x20ff
	s_cbranch_scc0 .LBB0_122
	s_cmpk_gt_u32 s3, 0x2bff
	s_cbranch_scc0 .LBB0_119
	s_cmpk_gt_u32 s3, 0x407f
	s_cbranch_scc0 .LBB0_116
	s_cmpk_gt_u32 s3, 0x587f
	s_cbranch_scc0 .LBB0_113
	s_cmpk_gt_u32 s3, 0x607f
	s_cbranch_scc0 .LBB0_110
	s_cmpk_gt_u32 s3, 0x687f
	s_cbranch_scc0 .LBB0_106
	s_load_dwordx2 s[14:15], s[10:11], 0xc8
	s_add_i32 s20, s3, 0xffff9780
	s_lshr_b32 s4, s20, 8
	s_and_b32 s42, s20, 0xff
	s_lshl_b64 s[20:21], s[4:5], 22
	s_waitcnt lgkmcnt(0)
	s_add_u32 s20, s14, s20
	s_addc_u32 s21, s15, s21
	s_lshl_b64 s[14:15], s[4:5], 21
	s_add_u32 s14, s30, s14
	s_addc_u32 s15, s31, s15
	s_mov_b64 s[22:23], 0
.LBB0_106:
	s_andn2_b64 vcc, exec, s[22:23]
	s_cbranch_vccnz .LBB0_108
	s_load_dwordx2 s[14:15], s[10:11], 0xd8
	s_add_i32 s22, s3, 0xffff9f80
	s_lshr_b32 s4, s22, 10
	s_and_b32 s42, s22, 0x3ff
	s_lshl_b64 s[20:21], s[4:5], 24
	s_waitcnt lgkmcnt(0)
	s_add_u32 s20, s14, s20
	s_addc_u32 s21, s15, s21
	s_lshr_b32 s4, s22, 9
	s_or_b32 s4, s4, 1
	s_lshl_b64 s[14:15], s[4:5], 23
	s_add_u32 s14, s34, s14
	s_addc_u32 s15, s35, s15
	s_cmp_eq_u32 s101, 0
	s_cselect_b32 s44, 0, 0x800
	s_mov_b32 s43, 32
	s_branch .LBB0_109

.LBB0_113:
	s_andn2_b64 vcc, exec, s[22:23]
	s_mov_b32 s45, s44
	s_cbranch_vccnz .LBB0_115
	s_add_i32 s4, s3, 0xffffbf80
	s_cmpk_gt_u32 s4, 0xbff
	s_cselect_b64 s[14:15], -1, 0
	s_and_b64 s[20:21], s[14:15], exec
	s_load_dwordx2 s[20:21], s[10:11], 0xd0
	s_cselect_b32 s22, 0xfffff400, 0
	s_add_i32 s42, s22, s4
	s_and_b64 s[22:23], s[14:15], exec
	s_cselect_b32 s4, 0x3000000, 0
	s_waitcnt lgkmcnt(0)
	s_add_u32 s20, s20, s4
	s_addc_u32 s21, s21, 0
	s_and_b64 s[14:15], s[14:15], exec
	s_cselect_b32 s4, s39, 0x1800000
	s_add_u32 s14, s36, s4
	s_addc_u32 s15, s37, 0
	s_movk_i32 s45, 0x800
	s_cmp_eq_u32 s101, 0
	s_cselect_b32 s44, 0, 0x1800
	s_movk_i32 s43, 0x60

.LBB0_259:
	s_or_b64 exec, exec, s[20:21]
	s_waitcnt lgkmcnt(0)
	s_andn2_b64 vcc, exec, s[18:19]
	s_cbranch_vccnz .LBB0_94
	s_add_i32 s3, s3, s29
	s_cmp_ge_i32 s3, s100
	s_cbranch_scc1 .LBB0_311
	s_cmpk_gt_i32 s3, 0xaff
	s_mov_b64 s[20:21], -1
	s_cbranch_scc0 .LBB0_292
	s_cmpk_gt_u32 s3, 0x15ff
	s_cbranch_scc0 .LBB0_289
	s_cmpk_gt_u32 s3, 0x20ff
	s_cbranch_scc0 .LBB0_286
	s_cmpk_gt_u32 s3, 0x2bff
	s_cbranch_scc0 .LBB0_283
	s_cmpk_gt_u32 s3, 0x407f
	s_cbranch_scc0 .LBB0_280
	s_cmpk_gt_u32 s3, 0x587f
	s_cbranch_scc0 .LBB0_277
	s_cmpk_gt_u32 s3, 0x607f
	s_cbranch_scc0 .LBB0_274
	s_cmpk_gt_u32 s3, 0x687f
	s_cbranch_scc0 .LBB0_270
	s_load_dwordx2 s[0:1], s[10:11], 0xc8
	s_add_i32 s18, s3, 0xffff9780
	s_lshr_b32 s4, s18, 8
	s_and_b32 s24, s18, 0xff
	s_lshl_b64 s[18:19], s[4:5], 22
	s_waitcnt lgkmcnt(0)
	s_add_u32 s18, s0, s18
	s_addc_u32 s19, s1, s19
	s_lshl_b64 s[0:1], s[4:5], 21
	s_add_u32 s0, s30, s0
	s_addc_u32 s1, s31, s1
	s_mov_b64 s[20:21], 0
.LBB0_270:
	s_andn2_b64 vcc, exec, s[20:21]
	s_cbranch_vccnz .LBB0_272
	s_load_dwordx2 s[0:1], s[10:11], 0xd8
	s_add_i32 s20, s3, 0xffff9f80
	s_lshr_b32 s4, s20, 10
	s_and_b32 s24, s20, 0x3ff
	s_lshl_b64 s[18:19], s[4:5], 24
	s_waitcnt lgkmcnt(0)
	s_add_u32 s18, s0, s18
	s_addc_u32 s19, s1, s19
	s_lshr_b32 s0, s20, 9
	s_or_b32 s4, s0, 1
	s_lshl_b64 s[0:1], s[4:5], 23
	s_add_u32 s0, s34, s0
	s_addc_u32 s1, s35, s1
	s_cmp_eq_u32 s101, 0
	s_cselect_b32 s25, 0, 0x800
	s_mov_b32 s26, 32
	s_branch .LBB0_273

.LBB0_277:
	s_andn2_b64 vcc, exec, s[20:21]
	s_mov_b32 s27, s25
	s_cbranch_vccnz .LBB0_279
	s_add_i32 s4, s3, 0xffffbf80
	s_cmpk_gt_u32 s4, 0xbff
	s_cselect_b64 s[0:1], -1, 0
	s_and_b64 s[18:19], s[0:1], exec
	s_load_dwordx2 s[18:19], s[10:11], 0xd0
	s_cselect_b32 s20, 0xfffff400, 0
	s_add_i32 s24, s20, s4
	s_and_b64 s[20:21], s[0:1], exec
	s_cselect_b32 s4, 0x3000000, 0
	s_waitcnt lgkmcnt(0)
	s_add_u32 s18, s18, s4
	s_addc_u32 s19, s19, 0
	s_and_b64 s[0:1], s[0:1], exec
	s_cselect_b32 s0, s39, 0x1800000
	s_add_u32 s0, s36, s0
	s_addc_u32 s1, s37, 0
	s_movk_i32 s27, 0x800
	s_cmp_eq_u32 s101, 0
	s_cselect_b32 s25, 0, 0x1800
	s_movk_i32 s26, 0x60

; #define GAS __attribute__((address_space(1)))
; __device__ __forceinline__ unsigned xb_ld(unsigned* p)              { return __hip_atomic_load(p, __ATOMIC_RELAXED, __HIP_MEMORY_SCOPE_AGENT); }
; #define XB_SPIN(cond, bar) do { unsigned _sp = 0; while (cond) { __builtin_amdgcn_s_sleep(1); \
;     if ((++_sp & 255u) == 0u) { if (xb_ld(&(bar)[XB_TMO])) break; if (_sp > XB_SPIN_CAP) { atomicAdd(&(bar)[XB_TMO], 1u); break; } } } } while (0)
; #define RUN(k, ...) do { if (EN(k)) { const int nr_ = 1 + (int)((rep_mask >> (k)) & 1u); _Pragma("nounroll") for (int r_ = 0; r_ < nr_; ++r_) { __VA_ARGS__; if (r_ + 1 < nr_) GRID_BAR(); } } } while (0)
; #define RUN(k, ...) do { if (EN(k)) { __VA_ARGS__; } } while (0)
; #define SEAM(k) do { if ((k) + 1 < hi) GRID_BAR(); } while (0)
; #define PH_ARGS KArgs ap = kargs(); unsigned char* ws = (unsigned char*)(GAS unsigned char*)ap->ws; (void)ws;     int Gp = gridDim.x; asm volatile("" : "+s"(Gp)); const int G = Gp; (void)G
; __device__ __forceinline__ void p0a_phase(LAS unsigned char* lds, KArgs A, int G, int wave_s) {
;     ...
;         TR_PIPELINE(gw, NITEMS, NGW, P0_DECODE);
;     ...
;     }
; }
; __global__ void __launch_bounds__(512, 2) fwd(Args args) {
;     ...
;     if (IN(0)) { PH_ARGS; RUN(0, p0a_phase(lds, ap, G, wave_s)); if (!IN(1)) SEAM(0); }
;     if (IN(1)) { PH_ARGS;
;         if (wave_s == 0) { unsigned* rdy = (unsigned*)(GAS unsigned*)((unsigned*)(ws + WS_CTL) + CW_MODRDY); XB_SPIN(xb_ld(rdy) < 16u, bar.bar);
.Ldef_return:
	s_cmp_eq_u32 s101, 2
	s_cbranch_scc1 .Ldef_gate2
	v_readlane_b32 s0, v247, 0
	v_readlane_b32 s1, v247, 1
	v_readlane_b32 s2, v247, 2
	v_readlane_b32 s3, v247, 3
	v_readlane_b32 s4, v247, 4
	v_readlane_b32 s5, v247, 5
	v_readlane_b32 s6, v247, 6
	v_readlane_b32 s7, v247, 7
	v_readlane_b32 s8, v247, 8
	v_readlane_b32 s9, v247, 9
	v_readlane_b32 s10, v247, 10
	v_readlane_b32 s11, v247, 11
	v_readlane_b32 s12, v247, 12
	v_readlane_b32 s13, v247, 13
	v_readlane_b32 s14, v247, 14
	v_readlane_b32 s15, v247, 15
	v_readlane_b32 s16, v247, 16
	v_readlane_b32 s17, v247, 17
	v_readlane_b32 s18, v247, 18
	v_readlane_b32 s19, v247, 19
	v_readlane_b32 s20, v247, 20
	v_readlane_b32 s21, v247, 21
	v_readlane_b32 s22, v247, 22
	v_readlane_b32 s23, v247, 23
	v_readlane_b32 s24, v247, 24
	v_readlane_b32 s25, v247, 25
	v_readlane_b32 s26, v247, 26
	v_readlane_b32 s27, v247, 27
	v_readlane_b32 s28, v247, 28
	v_readlane_b32 s29, v247, 29
	v_readlane_b32 s30, v247, 30
	v_readlane_b32 s31, v247, 31
	v_readlane_b32 s32, v247, 32
	v_readlane_b32 s33, v247, 33
	v_readlane_b32 s34, v247, 34
	v_readlane_b32 s35, v247, 35
	v_readlane_b32 s36, v247, 36
	v_readlane_b32 s37, v247, 37
	v_readlane_b32 s38, v247, 38
	v_readlane_b32 s39, v247, 39
	v_readlane_b32 s40, v247, 40
	v_readlane_b32 s41, v247, 41
	v_readlane_b32 s42, v247, 42
	v_readlane_b32 s43, v247, 43
	v_readlane_b32 s44, v247, 44
	v_readlane_b32 s45, v247, 45
	v_readlane_b32 s46, v247, 46
	v_readlane_b32 s47, v247, 47
	v_readlane_b32 s48, v247, 48
	v_readlane_b32 s49, v247, 49
	v_readlane_b32 s50, v247, 50
	v_mov_b32_e32 v1, 0
	s_cmp_eq_u32 s101, 1
	s_mov_b32 s101, 0
	s_cbranch_scc1 .LBB0_1572
	s_branch .Lisl_gate_ret
.Ldef_gate2:
	v_readlane_b32 s0, v254, 53
	s_lshr_b32 s0, s0, 1
	s_lshl_b32 s3, s0, 10
	s_addk_i32 s3, 0x6080
	s_add_i32 s100, s3, 0x400
	s_mov_b32 s101, 3
.Ldef_entry:
	s_mov_b64 s[10:11], s[90:91]
	s_load_dwordx2 s[16:17], s[10:11], 0x118
	v_readlane_b32 s20, v254, 48
	v_mbcnt_lo_u32_b32 v64, -1, 0
	v_mbcnt_hi_u32_b32 v64, -1, v64
	s_lshr_b32 s20, s20, 6
	s_movk_i32 s29, 0x80
	v_readlane_b32 s0, v253, 0
	s_and_b32 s0, s0, 0x7f
	s_lshl_b32 s0, s0, 3
	s_add_i32 s3, s3, s0
	s_add_i32 s3, s3, s20
	s_waitcnt lgkmcnt(0)
	s_cmp_lt_i32 s3, s100
	v_lshrrev_b32_e32 v133, 4, v64
	v_lshlrev_b32_e32 v0, 2, v64
	v_readlane_b32 s1, v253, 1
	s_cbranch_scc1 .LBB0_33
	s_branch .Lp0_bb31
.LBB0_421:
	s_cmp_eq_u32 s101, 0
	s_cbranch_scc0 .Ldef_return
	s_cmp_lt_i32 s94, 2
	s_cselect_b64 s[0:1], -1, 0
	s_cmp_gt_i32 s95, 1
	s_cselect_b64 s[4:5], -1, 0
	s_and_b64 s[0:1], s[0:1], s[4:5]
	s_and_b64 vcc, exec, s[0:1]
	s_cbranch_vccnz .LBB0_423
	s_add_u32 s78, s90, 0x130
	s_addc_u32 s79, s91, 0
	s_and_b32 s89, s38, 0xffffffc0
	s_cbranch_execz .LBB0_424
	s_branch .LBB0_490

; #define RUN(k, ...) do { if (EN(k)) { const int nr_ = 1 + (int)((rep_mask >> (k)) & 1u); _Pragma("nounroll") for (int r_ = 0; r_ < nr_; ++r_) { __VA_ARGS__; if (r_ + 1 < nr_) GRID_BAR(); } } } while (0)
; #define RUN(k, ...) do { if (EN(k)) { __VA_ARGS__; } } while (0)
; #define SEAM(k) do { if ((k) + 1 < hi) GRID_BAR(); } while (0)
; #define PH_ARGS KArgs ap = kargs(); unsigned char* ws = (unsigned char*)(GAS unsigned char*)ap->ws; (void)ws;     int Gp = gridDim.x; asm volatile("" : "+s"(Gp)); const int G = Gp; (void)G
; __global__ void __launch_bounds__(512, 2) fwd(Args args) {
;     ...
;             if (IN(p)) { PH_ARGS;
;                 const int first = (G >= 256) ? 128 : 0;
;                 RUN(5, if ((int)blockIdx.x < 128 || first == 0) dn_scan_phase(lds, W_CHU, W_CHW, W_CHQD, W_CHKT, W_CHA, W_CHGL, W_ODN, (first == 0) ? G : 128, wave_s));
;                 RUN(6, if ((int)blockIdx.x >= first) s5_phase(lds, W_PROJ, KIN(17) + (size_t)j * 4096, KIN(18) + (size_t)j * 4096, KIN(19) + (size_t)j * 65536, KIN(20) + (size_t)j * 65536,
;                                                               KIN(21) + (size_t)j * 65536, KIN(22) + (size_t)j * 65536, KIN(23) + (size_t)j * 1024, KIN(24) + (size_t)j * 64, W_YPRE, first, G - first, wave_s));
;                 SEAM(p);
.Ldef_scan:
	v_writelane_b32 v247, s0, 0
	v_writelane_b32 v247, s1, 1
	v_writelane_b32 v247, s2, 2
	v_writelane_b32 v247, s3, 3
	v_writelane_b32 v247, s4, 4
	v_writelane_b32 v247, s5, 5
	v_writelane_b32 v247, s6, 6
	v_writelane_b32 v247, s7, 7
	v_writelane_b32 v247, s8, 8
	v_writelane_b32 v247, s9, 9
	v_writelane_b32 v247, s10, 10
	v_writelane_b32 v247, s11, 11
	v_writelane_b32 v247, s12, 12
	v_writelane_b32 v247, s13, 13
	v_writelane_b32 v247, s14, 14
	v_writelane_b32 v247, s15, 15
	v_writelane_b32 v247, s16, 16
	v_writelane_b32 v247, s17, 17
	v_writelane_b32 v247, s18, 18
	v_writelane_b32 v247, s19, 19
	v_writelane_b32 v247, s20, 20
	v_writelane_b32 v247, s21, 21
	v_writelane_b32 v247, s22, 22
	v_writelane_b32 v247, s23, 23
	v_writelane_b32 v247, s24, 24
	v_writelane_b32 v247, s25, 25
	v_writelane_b32 v247, s26, 26
	v_writelane_b32 v247, s27, 27
	v_writelane_b32 v247, s28, 28
	v_writelane_b32 v247, s29, 29
	v_writelane_b32 v247, s30, 30
	v_writelane_b32 v247, s31, 31
	v_writelane_b32 v247, s32, 32
	v_writelane_b32 v247, s33, 33
	v_writelane_b32 v247, s34, 34
	v_writelane_b32 v247, s35, 35
	v_writelane_b32 v247, s36, 36
	v_writelane_b32 v247, s37, 37
	v_writelane_b32 v247, s38, 38
	v_writelane_b32 v247, s39, 39
	v_writelane_b32 v247, s40, 40
	v_writelane_b32 v247, s41, 41
	v_writelane_b32 v247, s42, 42
	v_writelane_b32 v247, s43, 43
	v_writelane_b32 v247, s44, 44
	v_writelane_b32 v247, s45, 45
	v_writelane_b32 v247, s46, 46
	v_writelane_b32 v247, s47, 47
	v_writelane_b32 v247, s48, 48
	v_writelane_b32 v247, s49, 49
	v_writelane_b32 v247, s50, 50
	s_waitcnt lgkmcnt(0)
	s_barrier
	v_readlane_b32 s0, v254, 53
	s_lshr_b32 s0, s0, 1
	s_mul_i32 s3, s0, 0xc00
	s_addk_i32 s3, 0x4080
	s_add_i32 s100, s3, 0x800
	s_mov_b32 s101, 1
	s_branch .Ldef_entry

; __device__ __forceinline__ int fresh_lane() { int l; asm volatile("v_mbcnt_lo_u32_b32 %0, -1, 0\n\tv_mbcnt_hi_u32_b32 %0, -1, %0" : "=v"(l)); return l; }
; #define LAS __attribute__((address_space(3)))
; #define RUN(k, ...) do { if (EN(k)) { const int nr_ = 1 + (int)((rep_mask >> (k)) & 1u); _Pragma("nounroll") for (int r_ = 0; r_ < nr_; ++r_) { __VA_ARGS__; if (r_ + 1 < nr_) GRID_BAR(); } } } while (0)
; __device__ __forceinline__ void s5_phase(LAS unsigned char* lds, const bf16* PROJ, const float* a_re, const float* a_im, const float* b_re, const float* b_im, const float* c_re, const float* c_im, ...
;     int tid_ = wave_s * 64 + fresh_lane(); asm volatile("" : "+v"(tid_)); const int tid = tid_, lane = tid & 63, w = __builtin_amdgcn_readfirstlane(tid >> 6), q4 = lane >> 4, l15 = lane & 15;
;     LAS unsigned char* UL = lds;
;     LAS float* EL = (LAS float*)(lds + 33792);
;     LAS unsigned char* S0L = lds + 67584;
;     LAS unsigned short* KTAB = (LAS unsigned short*)(lds + 84992);
;     LAS f32x2* POW = (LAS f32x2*)(lds + 33792);
;     LAS f32x2* BB = (LAS f32x2*)(lds + 42496);
;     LAS f32x2* CC = (LAS f32x2*)(lds + 50688);
;     bf16x8 afA[8], afC[2][4]; f32x2 a16 = (f32x2){0.f, 0.f}; int g_prev = -1;
;     v4u upre[4]; bool have = false;
;     for (int bi = (int)blockIdx.x - first; bi < 256; bi += nblk) {
;         const int b = bi >> 6, g = ((bi & 7) << 3) | ((bi >> 3) & 7);
;         if (!have) {
; #pragma unroll
;             for (int k = 0; k < 4; ++k) { const int idx = tid + 512 * k, tok = idx >> 1, hf = idx & 1; upre[k] = *(const v4u*)(PROJ + ((size_t)b * SEQ + tok) * PLD + 4096 + 16 * g + 8 * hf); } }
; __global__ void __launch_bounds__(512, 2) fwd(Args args) {
;     ...
;             if (IN(p)) { PH_ARGS;
;                 const int first = (G >= 256) ? 128 : 0;
;                 RUN(5, if ((int)blockIdx.x < 128 || first == 0) dn_scan_phase(lds, W_CHU, W_CHW, W_CHQD, W_CHKT, W_CHA, W_CHGL, W_ODN, (first == 0) ? G : 128, wave_s));
;                 RUN(6, if ((int)blockIdx.x >= first) s5_phase(lds, W_PROJ, KIN(17) + (size_t)j * 4096, KIN(18) + (size_t)j * 4096, KIN(19) + (size_t)j * 65536, KIN(20) + (size_t)j * 65536,
;                                                               KIN(21) + (size_t)j * 65536, KIN(22) + (size_t)j * 65536, KIN(23) + (size_t)j * 1024, KIN(24) + (size_t)j * 64, W_YPRE, first, G - first, wave_s));
.Lisl_gate_ret:
	s_branch .LBB0_1648
.LBB0_1357:
	s_and_b64 s[8:9], s[8:9], exec
	s_cselect_b32 s8, 0, 0x80
	v_readlane_b32 s10, v253, 0
	s_cmp_lt_i32 s10, s8
	v_readlane_b32 s11, v253, 1
	s_cbranch_scc1 .Ldef_scan
	v_readlane_b32 s10, v253, 0
	v_mbcnt_lo_u32_b32 v0, -1, 0
	v_mbcnt_hi_u32_b32 v0, -1, v0
	s_sub_i32 s37, s10, s8
	v_add_u32_e32 v220, s89, v0
	s_cmpk_gt_i32 s37, 0xff
	v_readfirstlane_b32 s9, v220
	v_readlane_b32 s11, v253, 1
	s_cbranch_scc1 .LBB0_1572
	v_writelane_b32 v255, s48, 27
	s_load_dwordx16 s[40:55], s[6:7], 0x88
	v_readlane_b32 s12, v254, 57
	v_readlane_b32 s13, v254, 58
	s_add_u32 s16, s0, 0x1ee00000
	s_mov_b32 s13, s81
	s_addc_u32 s17, s1, 0
	s_lshl_b64 s[6:7], s[12:13], 12
	s_lshl_b64 s[10:11], s[12:13], 14
	s_waitcnt lgkmcnt(0)
	s_add_u32 s58, s40, s10
	s_addc_u32 s59, s41, s11
	s_add_u32 s60, s42, s10
	s_addc_u32 s61, s43, s11
	s_add_u32 s62, s52, s6
	s_mov_b32 s6, s12
	s_addc_u32 s63, s53, s7
	v_writelane_b32 v254, s6, 57
	v_lshlrev_b32_e32 v3, 4, v220
	s_waitcnt vmcnt(0)
	v_and_b32_e32 v4, 0x1e0, v3
	v_writelane_b32 v254, s7, 58
	s_lshl_b64 s[6:7], s[12:13], 8
	s_add_u32 s6, s54, s6
	s_addc_u32 s7, s55, s7
	v_writelane_b32 v255, s6, 7
	s_add_u32 s0, s0, 0x30700000
	s_addc_u32 s1, s1, 0
	v_writelane_b32 v255, s7, 8
	v_writelane_b32 v255, s0, 1
	s_ashr_i32 s65, s9, 6
	s_lshl_b32 s6, s65, 3
	v_writelane_b32 v255, s1, 2
	s_sub_i32 s0, s26, s8
	v_writelane_b32 v255, s0, 3
	v_readlane_b32 s0, v254, 53
	v_readlane_b32 s1, v254, 54
	s_lshl_b64 s[0:1], s[0:1], 17
	v_writelane_b32 v255, s6, 9
	s_and_b32 s6, s9, 0xffffffc0
	s_and_b32 s0, s0, 0xfffc0000
	s_sub_i32 s64, 15, s65
	s_add_i32 s66, s6, 0
	s_cmp_lt_u32 s9, 64
	s_cselect_b64 s[68:69], -1, 0
	s_lshl_b32 s6, s65, 9
	v_writelane_b32 v255, s6, 13
	s_add_i32 s6, s6, 0
	v_writelane_b32 v255, s6, 4
	s_lshl_b32 s6, s64, 9
	v_writelane_b32 v255, s6, 14
	s_add_i32 s6, s6, 0
	s_cmp_eq_u32 s65, 15
	v_writelane_b32 v255, s6, 10
	s_cselect_b64 s[70:71], -1, 0
	s_ashr_i32 s6, s65, 31
	s_cmp_gt_i32 s65, -1
	s_cselect_b64 s[84:85], -1, 0
	s_cmp_gt_i32 s65, 1
	s_cselect_b64 s[72:73], -1, 0
	s_cmp_gt_i32 s65, 3
	s_cselect_b64 s[82:83], -1, 0
	s_cmp_gt_i32 s65, 5
	s_cselect_b64 s[96:97], -1, 0
	s_cmp_gt_i32 s65, 7
	s_cselect_b64 s[86:87], -1, 0
	s_cmp_gt_i32 s65, 9
	s_cselect_b64 s[12:13], -1, 0
	s_cmp_gt_i32 s65, 11
	s_cselect_b64 s[14:15], -1, 0
	s_cmp_gt_i32 s65, 13
	v_writelane_b32 v255, s6, 51
	s_cselect_b64 s[18:19], -1, 0
	s_ashr_i32 s6, s64, 31
	s_cmp_lt_i32 s65, 16
	s_cselect_b64 s[20:21], -1, 0
	s_cmp_lt_i32 s65, 14
	s_cselect_b64 s[94:95], -1, 0
	s_cmp_lt_i32 s65, 12
	s_cselect_b64 s[10:11], -1, 0
	s_cmp_lt_i32 s65, 10
	s_cselect_b64 s[90:91], -1, 0
	s_cmp_lt_i32 s65, 8
	s_cselect_b64 s[76:77], -1, 0
	s_cmp_lt_i32 s65, 6
	s_cselect_b64 s[88:89], -1, 0
	s_cmp_lt_i32 s65, 4
	s_cselect_b64 s[92:93], -1, 0
	s_cmp_lt_i32 s65, 2
	v_writelane_b32 v255, s6, 5
	s_cselect_b64 s[6:7], -1, 0
	s_add_i32 s9, 0, 0x8400
	s_add_u32 s27, s44, s0
	v_writelane_b32 v255, s27, 19
	s_addc_u32 s27, s45, s1
	s_lshl_b32 s8, s8, 3
	s_lshl_b32 s26, s26, 3
	v_writelane_b32 v255, s27, 20
	s_sub_i32 s26, s26, s8
	v_writelane_b32 v255, s26, 6
	v_readlane_b32 s26, v253, 6
	s_sub_i32 s67, s26, s8
	s_add_u32 s8, s46, s0
	v_writelane_b32 v255, s8, 21
	s_addc_u32 s8, s47, s1
	v_writelane_b32 v255, s8, 22
	s_add_u32 s8, s48, s0
	v_writelane_b32 v255, s8, 23
	s_addc_u32 s8, s49, s1
	v_writelane_b32 v255, s8, 24
	s_add_u32 s0, s50, s0
	v_writelane_b32 v255, s0, 25
	s_addc_u32 s0, s51, s1
	v_writelane_b32 v255, s0, 26
	s_movk_i32 s0, 0x440
	v_cmp_gt_i32_e64 s[0:1], s0, v220
	v_and_b32_e32 v3, 16, v3
	v_add3_u32 v3, 0, v4, v3
	v_writelane_b32 v255, s0, 15
	v_add_u32_e32 v4, 0x200, v220
	v_add_u32_e32 v5, 0x400, v220
	v_writelane_b32 v255, s1, 16
	s_movk_i32 s0, 0x400
	v_cmp_gt_i32_e64 s[0:1], s0, v220
	v_add_u32_e32 v6, 0x600, v220
	v_ashrrev_i32_e32 v224, 1, v4
	v_writelane_b32 v255, s0, 17
	v_ashrrev_i32_e32 v226, 1, v5
	v_ashrrev_i32_e32 v228, 1, v6
	v_writelane_b32 v255, s1, 18
	v_ashrrev_i32_e32 v7, 5, v220
	s_movk_i32 s0, 0x210
	v_ashrrev_i32_e32 v4, 5, v4
	v_ashrrev_i32_e32 v5, 5, v5
	v_ashrrev_i32_e32 v6, 5, v6
	v_and_b32_e32 v238, 63, v220
	v_lshlrev_b32_e32 v0, 3, v220
	v_mul_lo_u32 v7, v7, s0
	v_mul_lo_u32 v4, v4, s0
	v_mul_lo_u32 v5, v5, s0
	v_mul_lo_u32 v6, v6, s0
	v_readlane_b32 s0, v254, 37
	v_and_b32_e32 v2, 8, v0
	v_lshl_add_u32 v239, v238, 3, 0
	v_ashrrev_i32_e32 v222, 1, v220
	v_add_u32_e32 v242, s9, v0
	v_add_u32_e32 v243, s0, v0
	v_ashrrev_i32_e32 v221, 31, v220
	v_mov_b32_e32 v0, v1
	v_add_u32_e32 v240, 0x8400, v239
	v_lshl_add_u32 v241, v238, 2, s22
	v_ashrrev_i32_e32 v223, 31, v222
	v_ashrrev_i32_e32 v225, 31, v224
	v_ashrrev_i32_e32 v227, 31, v226
	v_ashrrev_i32_e32 v229, 31, v228
	s_mov_b32 s52, -1
	v_lshlrev_b64 v[230:231], 2, v[220:221]
	s_mov_b64 s[48:49], 0
	v_lshlrev_b32_e32 v232, 1, v2
	v_add_u32_e32 v221, v3, v7
	v_add_u32_e32 v244, v3, v4
	v_add_u32_e32 v245, v3, v5
	v_add_u32_e32 v246, v3, v6
	v_mov_b64_e32 v[2:3], v[0:1]
	s_branch .LBB0_1361

; #define RUN(k, ...) do { if (EN(k)) { const int nr_ = 1 + (int)((rep_mask >> (k)) & 1u); _Pragma("nounroll") for (int r_ = 0; r_ < nr_; ++r_) { __VA_ARGS__; if (r_ + 1 < nr_) GRID_BAR(); } } } while (0)
; #define RUN(k, ...) do { if (EN(k)) { __VA_ARGS__; } } while (0)
; #define SEAM(k) do { if ((k) + 1 < hi) GRID_BAR(); } while (0)
; #define PH_ARGS KArgs ap = kargs(); unsigned char* ws = (unsigned char*)(GAS unsigned char*)ap->ws; (void)ws;     int Gp = gridDim.x; asm volatile("" : "+s"(Gp)); const int G = Gp; (void)G
; __global__ void __launch_bounds__(512, 2) fwd(Args args) {
;     ...
;             if (IN(p)) { PH_ARGS;
;                 pg8::Gemm g{W_YPRE, (const bf16*)(ws + WS_WGLU + j * WGLU_STRIDE), MTOK, 1024, 1024, wave_s}; pg8::StaticOrder S; S.init(MTOK, 1024, G, (int)blockIdx.x);
;                 pg8::EpiGlu E{W_YPRE, 1024, W_MIX, DM, 1024};
;                 RUN(7, pg8::gemm_phase<pg8::EpiGlu, pg8::StaticOrder, true, true>(lds, g, S, E));
;                 RUN(8, dn_gate_phase(W_ODN, W_PROJ, KIN(16) + j * 128, W_MIX, G, wave_s));
;                 SEAM(p);
;             }
.LBB0_1647:
	s_or_b64 exec, exec, s[0:1]
	v_writelane_b32 v247, s0, 0
	v_writelane_b32 v247, s1, 1
	v_writelane_b32 v247, s2, 2
	v_writelane_b32 v247, s3, 3
	v_writelane_b32 v247, s4, 4
	v_writelane_b32 v247, s5, 5
	v_writelane_b32 v247, s6, 6
	v_writelane_b32 v247, s7, 7
	v_writelane_b32 v247, s8, 8
	v_writelane_b32 v247, s9, 9
	v_writelane_b32 v247, s10, 10
	v_writelane_b32 v247, s11, 11
	v_writelane_b32 v247, s12, 12
	v_writelane_b32 v247, s13, 13
	v_writelane_b32 v247, s14, 14
	v_writelane_b32 v247, s15, 15
	v_writelane_b32 v247, s16, 16
	v_writelane_b32 v247, s17, 17
	v_writelane_b32 v247, s18, 18
	v_writelane_b32 v247, s19, 19
	v_writelane_b32 v247, s20, 20
	v_writelane_b32 v247, s21, 21
	v_writelane_b32 v247, s22, 22
	v_writelane_b32 v247, s23, 23
	v_writelane_b32 v247, s24, 24
	v_writelane_b32 v247, s25, 25
	v_writelane_b32 v247, s26, 26
	v_writelane_b32 v247, s27, 27
	v_writelane_b32 v247, s28, 28
	v_writelane_b32 v247, s29, 29
	v_writelane_b32 v247, s30, 30
	v_writelane_b32 v247, s31, 31
	v_writelane_b32 v247, s32, 32
	v_writelane_b32 v247, s33, 33
	v_writelane_b32 v247, s34, 34
	v_writelane_b32 v247, s35, 35
	v_writelane_b32 v247, s36, 36
	v_writelane_b32 v247, s37, 37
	v_writelane_b32 v247, s38, 38
	v_writelane_b32 v247, s39, 39
	v_writelane_b32 v247, s40, 40
	v_writelane_b32 v247, s41, 41
	v_writelane_b32 v247, s42, 42
	v_writelane_b32 v247, s43, 43
	v_writelane_b32 v247, s44, 44
	v_writelane_b32 v247, s45, 45
	v_writelane_b32 v247, s46, 46
	v_writelane_b32 v247, s47, 47
	v_writelane_b32 v247, s48, 48
	v_writelane_b32 v247, s49, 49
	v_writelane_b32 v247, s50, 50
	s_waitcnt lgkmcnt(0)
	s_barrier
	v_readlane_b32 s0, v254, 53
	s_lshr_b32 s0, s0, 1
	s_mul_i32 s3, s0, 0xc00
	s_addk_i32 s3, 0x4880
	s_add_i32 s100, s3, 0x400
	s_mov_b32 s101, 2
	s_branch .Lisl_gate_go
